# batched loads in win_tail/compress, pool items rebalanced over window groups, xcd barrier at phase 0, top-k via bitwise threshold search, transpose item rotation
# speedup vs baseline: 1.0157x; 1.0157x over previous
; DI void cmp_item(const Params& p, int item, LAS unsigned char* lds, int tid) {
;     ...
;     for (int tk = 0; tk < 4; ++tk) {
;         const int tt = t0 + tk, qb = tt >> 6, j = lane;
;         const float iv = impb[tk * 64 + j];
;         const bool valid = j <= qb, forced = (j == 0) || (j == qb) || (j == qb - 1);
;         const float sc = valid ? (forced ? 1e9f : iv) : -1e9f;
;         int rank = 0;
;         for (int jp = 0; jp < 64; ++jp) { const float o = __uint_as_float(__builtin_amdgcn_readlane(__float_as_uint(sc), jp)); rank += (o > sc || (o == sc && jp < j)) ? 1 : 0; }
;         const bool s = (rank < 16) && (sc > -1e8f);
;         const unsigned long long m = __ballot(s);
;         if (lane == 0) sel[tt] = m;
;     }
.LBB0_186:
	v_lshl_add_u32 v1, s4, 8, v0
	ds_read_b32 v1, v1
	v_mov_b32_e32 v2, 0x4e6e6b28
	s_mov_b32 s5, 0
	s_waitcnt lgkmcnt(0)
	v_cndmask_b32_e64 v1, v1, v2, s[8:9]
	v_mov_b32_e32 v2, 0xce6e6b28
	v_cndmask_b32_e32 v1, v1, v2, vcc
	v_add_f32_e32 v2, 0, v1
	v_ashrrev_i32_e32 v3, 31, v2
	v_or_b32_e32 v3, 0x80000000, v3
	v_xor_b32_e32 v2, v3, v2
	s_mov_b32 s5, 0
	s_or_b32 s15, s5, 0x80000000
	v_cmp_le_u32_e64 s[10:11], s15, v2
	s_bcnt1_i32_b64 s12, s[10:11]
	s_cmp_ge_u32 s12, 16
	s_cselect_b32 s5, s15, s5
	s_or_b32 s15, s5, 0x40000000
	v_cmp_le_u32_e64 s[10:11], s15, v2
	s_bcnt1_i32_b64 s12, s[10:11]
	s_cmp_ge_u32 s12, 16
	s_cselect_b32 s5, s15, s5
	s_or_b32 s15, s5, 0x20000000
	v_cmp_le_u32_e64 s[10:11], s15, v2
	s_bcnt1_i32_b64 s12, s[10:11]
	s_cmp_ge_u32 s12, 16
	s_cselect_b32 s5, s15, s5
	s_or_b32 s15, s5, 0x10000000
	v_cmp_le_u32_e64 s[10:11], s15, v2
	s_bcnt1_i32_b64 s12, s[10:11]
	s_cmp_ge_u32 s12, 16
	s_cselect_b32 s5, s15, s5
	s_or_b32 s15, s5, 0x8000000
	v_cmp_le_u32_e64 s[10:11], s15, v2
	s_bcnt1_i32_b64 s12, s[10:11]
	s_cmp_ge_u32 s12, 16
	s_cselect_b32 s5, s15, s5
	s_or_b32 s15, s5, 0x4000000
	v_cmp_le_u32_e64 s[10:11], s15, v2
	s_bcnt1_i32_b64 s12, s[10:11]
	s_cmp_ge_u32 s12, 16
	s_cselect_b32 s5, s15, s5
	s_or_b32 s15, s5, 0x2000000
	v_cmp_le_u32_e64 s[10:11], s15, v2
	s_bcnt1_i32_b64 s12, s[10:11]
	s_cmp_ge_u32 s12, 16
	s_cselect_b32 s5, s15, s5
	s_or_b32 s15, s5, 0x1000000
	v_cmp_le_u32_e64 s[10:11], s15, v2
	s_bcnt1_i32_b64 s12, s[10:11]
	s_cmp_ge_u32 s12, 16
	s_cselect_b32 s5, s15, s5
	s_or_b32 s15, s5, 0x800000
	v_cmp_le_u32_e64 s[10:11], s15, v2
	s_bcnt1_i32_b64 s12, s[10:11]
	s_cmp_ge_u32 s12, 16
	s_cselect_b32 s5, s15, s5
	s_or_b32 s15, s5, 0x400000
	v_cmp_le_u32_e64 s[10:11], s15, v2
	s_bcnt1_i32_b64 s12, s[10:11]
	s_cmp_ge_u32 s12, 16
	s_cselect_b32 s5, s15, s5
	s_or_b32 s15, s5, 0x200000
	v_cmp_le_u32_e64 s[10:11], s15, v2
	s_bcnt1_i32_b64 s12, s[10:11]
	s_cmp_ge_u32 s12, 16
	s_cselect_b32 s5, s15, s5
	s_or_b32 s15, s5, 0x100000
	v_cmp_le_u32_e64 s[10:11], s15, v2
	s_bcnt1_i32_b64 s12, s[10:11]
	s_cmp_ge_u32 s12, 16
	s_cselect_b32 s5, s15, s5
	s_or_b32 s15, s5, 0x80000
	v_cmp_le_u32_e64 s[10:11], s15, v2
	s_bcnt1_i32_b64 s12, s[10:11]
	s_cmp_ge_u32 s12, 16
	s_cselect_b32 s5, s15, s5
	s_or_b32 s15, s5, 0x40000
	v_cmp_le_u32_e64 s[10:11], s15, v2
	s_bcnt1_i32_b64 s12, s[10:11]
	s_cmp_ge_u32 s12, 16
	s_cselect_b32 s5, s15, s5
	s_or_b32 s15, s5, 0x20000
	v_cmp_le_u32_e64 s[10:11], s15, v2
	s_bcnt1_i32_b64 s12, s[10:11]
	s_cmp_ge_u32 s12, 16
	s_cselect_b32 s5, s15, s5
	s_or_b32 s15, s5, 0x10000
	v_cmp_le_u32_e64 s[10:11], s15, v2
	s_bcnt1_i32_b64 s12, s[10:11]
	s_cmp_ge_u32 s12, 16
	s_cselect_b32 s5, s15, s5
	s_or_b32 s15, s5, 0x8000
	v_cmp_le_u32_e64 s[10:11], s15, v2
	s_bcnt1_i32_b64 s12, s[10:11]
	s_cmp_ge_u32 s12, 16
	s_cselect_b32 s5, s15, s5
	s_or_b32 s15, s5, 0x4000
	v_cmp_le_u32_e64 s[10:11], s15, v2
	s_bcnt1_i32_b64 s12, s[10:11]
	s_cmp_ge_u32 s12, 16
	s_cselect_b32 s5, s15, s5
	s_or_b32 s15, s5, 0x2000
	v_cmp_le_u32_e64 s[10:11], s15, v2
	s_bcnt1_i32_b64 s12, s[10:11]
	s_cmp_ge_u32 s12, 16
	s_cselect_b32 s5, s15, s5
	s_or_b32 s15, s5, 0x1000
	v_cmp_le_u32_e64 s[10:11], s15, v2
	s_bcnt1_i32_b64 s12, s[10:11]
	s_cmp_ge_u32 s12, 16
	s_cselect_b32 s5, s15, s5
	s_or_b32 s15, s5, 0x800
	v_cmp_le_u32_e64 s[10:11], s15, v2
	s_bcnt1_i32_b64 s12, s[10:11]
	s_cmp_ge_u32 s12, 16
	s_cselect_b32 s5, s15, s5
	s_or_b32 s15, s5, 0x400
	v_cmp_le_u32_e64 s[10:11], s15, v2
	s_bcnt1_i32_b64 s12, s[10:11]
	s_cmp_ge_u32 s12, 16
	s_cselect_b32 s5, s15, s5
	s_or_b32 s15, s5, 0x200
	v_cmp_le_u32_e64 s[10:11], s15, v2
	s_bcnt1_i32_b64 s12, s[10:11]
	s_cmp_ge_u32 s12, 16
	s_cselect_b32 s5, s15, s5
	s_or_b32 s15, s5, 0x100
	v_cmp_le_u32_e64 s[10:11], s15, v2
	s_bcnt1_i32_b64 s12, s[10:11]
	s_cmp_ge_u32 s12, 16
	s_cselect_b32 s5, s15, s5
	s_or_b32 s15, s5, 0x80
	v_cmp_le_u32_e64 s[10:11], s15, v2
	s_bcnt1_i32_b64 s12, s[10:11]
	s_cmp_ge_u32 s12, 16
	s_cselect_b32 s5, s15, s5
	s_or_b32 s15, s5, 0x40
	v_cmp_le_u32_e64 s[10:11], s15, v2
	s_bcnt1_i32_b64 s12, s[10:11]
	s_cmp_ge_u32 s12, 16
	s_cselect_b32 s5, s15, s5
	s_or_b32 s15, s5, 0x20
	v_cmp_le_u32_e64 s[10:11], s15, v2
	s_bcnt1_i32_b64 s12, s[10:11]
	s_cmp_ge_u32 s12, 16
	s_cselect_b32 s5, s15, s5
	s_or_b32 s15, s5, 0x10
	v_cmp_le_u32_e64 s[10:11], s15, v2
	s_bcnt1_i32_b64 s12, s[10:11]
	s_cmp_ge_u32 s12, 16
	s_cselect_b32 s5, s15, s5
	s_or_b32 s15, s5, 0x8
	v_cmp_le_u32_e64 s[10:11], s15, v2
	s_bcnt1_i32_b64 s12, s[10:11]
	s_cmp_ge_u32 s12, 16
	s_cselect_b32 s5, s15, s5
	s_or_b32 s15, s5, 0x4
	v_cmp_le_u32_e64 s[10:11], s15, v2
	s_bcnt1_i32_b64 s12, s[10:11]
	s_cmp_ge_u32 s12, 16
	s_cselect_b32 s5, s15, s5
	s_or_b32 s15, s5, 0x2
	v_cmp_le_u32_e64 s[10:11], s15, v2
	s_bcnt1_i32_b64 s12, s[10:11]
	s_cmp_ge_u32 s12, 16
	s_cselect_b32 s5, s15, s5
	s_or_b32 s15, s5, 0x1
	v_cmp_le_u32_e64 s[10:11], s15, v2
	s_bcnt1_i32_b64 s12, s[10:11]
	s_cmp_ge_u32 s12, 16
	s_cselect_b32 s5, s15, s5
	v_cmp_lt_u32_e64 s[10:11], s5, v2
	v_cmp_eq_u32_e64 s[12:13], s5, v2
	s_bcnt1_i32_b64 s14, s[10:11]
	s_sub_i32 s14, 16, s14
	v_mbcnt_lo_u32_b32 v3, s12, 0
	v_mbcnt_hi_u32_b32 v3, s13, v3
	v_cmp_gt_u32_e64 s[100:101], s14, v3
	s_and_b64 s[12:13], s[12:13], s[100:101]
	s_or_b64 s[10:11], s[10:11], s[12:13]
	s_mov_b32 s5, 0xccbebc20
	v_cmp_lt_f32_e64 s[12:13], s5, v1
	s_and_b64 s[12:13], s[10:11], s[12:13]
	s_and_saveexec_b64 s[10:11], s[6:7]
	s_cbranch_execz .LBB0_185
	v_or_b32_e32 v2, s4, v108
	v_ashrrev_i32_e32 v3, 31, v2
	v_lshl_add_u64 v[2:3], v[2:3], 3, s[16:17]
	v_mov_b64_e32 v[4:5], s[12:13]
	global_store_dwordx2 v[2:3], v[4:5], off
	s_branch .LBB0_185

; #define CMPR_LOAD(A_, B_, S_) do { const int ks_ = kquart * 32 + (S_); A_ = *(const bf16x8*)(abase + (size_t)(ks_ >> 2) * NINP + (ks_ & 3) * 32); \
;         _Pragma("unroll") for (int c = 0; c < 8; ++c) B_[c] = *(const bf16x8*)(bbase + (size_t)c * 16 * 4096 + ks_ * 32); } while (0)
; #define CMPR_MMA(A_, B_) do { _Pragma("unroll") for (int c = 0; c < 8; ++c) acc[c] = __builtin_amdgcn_mfma_f32_16x16x32_bf16(A_, B_[c], acc[c], 0, 0, 0); } while (0)
; DI void compress_item(const Params& p, int L, int item, LAS unsigned char* lds, int tid) {
;     ...
;     bf16x8 a0, a1, b0[8], b1[8];
;     CMPR_LOAD(a0, b0, 0);
; #pragma unroll 1
;     for (int s = 0; s < 32; s += 2) {
;         CMPR_LOAD(a1, b1, s + 1);
;         __builtin_amdgcn_sched_barrier(0);
;         CMPR_MMA(a0, b0);
;         __builtin_amdgcn_sched_barrier(0);
;         if (s + 2 < 32) CMPR_LOAD(a0, b0, s + 2);
;         __builtin_amdgcn_sched_barrier(0);
;         CMPR_MMA(a1, b1);
;         __builtin_amdgcn_sched_barrier(0);
;     }
.LBB0_254:
	s_add_i32 s19, s15, s20
	s_add_i32 s16, s19, 1
	s_ashr_i32 s16, s16, 2
	v_mad_i64_i32 v[68:69], s[16:17], s16, v230, v[104:105]
	s_sub_i32 s16, s18, 32
	s_and_b32 s16, s16, 0x60
	s_lshl_b32 s84, s16, 1
	s_mov_b32 s16, 0xfff20000
	v_add_co_u32_e32 v72, vcc, s16, v110
	s_mov_b32 s16, 0xfff40000
	s_nop 0
	v_addc_co_u32_e32 v73, vcc, -1, v111, vcc
	v_add_co_u32_e32 v76, vcc, s16, v110
	s_mov_b32 s16, 0xfff60000
	s_nop 0
	v_addc_co_u32_e32 v77, vcc, -1, v111, vcc
	v_add_co_u32_e32 v80, vcc, s16, v110
	s_mov_b32 s16, 0xfff80000
	s_nop 0
	v_addc_co_u32_e32 v81, vcc, -1, v111, vcc
	v_add_co_u32_e32 v84, vcc, s16, v110
	s_mov_b32 s16, 0xfffa0000
	s_nop 0
	v_addc_co_u32_e32 v85, vcc, -1, v111, vcc
	v_add_co_u32_e32 v88, vcc, s16, v110
	s_mov_b32 s16, 0xfffc0000
	s_nop 0
	v_addc_co_u32_e32 v89, vcc, -1, v111, vcc
	v_add_co_u32_e32 v92, vcc, s16, v110
	s_mov_b32 s16, 0xfffe0000
	s_nop 0
	v_addc_co_u32_e32 v93, vcc, -1, v111, vcc
	v_add_co_u32_e32 v96, vcc, s16, v110
	v_lshl_add_u64 v[68:69], v[68:69], 0, s[84:85]
	s_nop 0
	v_addc_co_u32_e32 v97, vcc, -1, v111, vcc
	global_load_dwordx4 v[68:71], v[68:69], off
	s_nop 0
	global_load_dwordx4 v[72:75], v[72:73], off
	s_nop 0
	global_load_dwordx4 v[76:79], v[76:77], off
	s_nop 0
	global_load_dwordx4 v[80:83], v[80:81], off
	s_nop 0
	global_load_dwordx4 v[84:87], v[84:85], off
	s_nop 0
	global_load_dwordx4 v[88:91], v[88:89], off
	s_nop 0
	global_load_dwordx4 v[92:95], v[92:93], off
	s_nop 0
	global_load_dwordx4 v[96:99], v[96:97], off
	s_nop 0
	global_load_dwordx4 v[100:103], v[110:111], off
	s_waitcnt vmcnt(16)
	v_mfma_f32_16x16x32_bf16 v[0:3], v[28:31], v[36:39], v[0:3]
	s_waitcnt vmcnt(15)
	v_mfma_f32_16x16x32_bf16 v[4:7], v[28:31], v[40:43], v[4:7]
	s_waitcnt vmcnt(14)
	v_mfma_f32_16x16x32_bf16 v[8:11], v[28:31], v[44:47], v[8:11]
	s_waitcnt vmcnt(13)
	v_mfma_f32_16x16x32_bf16 v[12:15], v[28:31], v[48:51], v[12:15]
	s_waitcnt vmcnt(12)
	v_mfma_f32_16x16x32_bf16 v[16:19], v[28:31], v[52:55], v[16:19]
	s_waitcnt vmcnt(11)
	v_mfma_f32_16x16x32_bf16 v[20:23], v[28:31], v[56:59], v[20:23]
	s_waitcnt vmcnt(10)
	v_mfma_f32_16x16x32_bf16 v[24:27], v[28:31], v[60:63], v[24:27]
	s_waitcnt vmcnt(9)
	v_mfma_f32_16x16x32_bf16 v[32:35], v[28:31], v[64:67], v[32:35]
	s_cmp_gt_u32 s20, 29
	s_cselect_b64 s[16:17], -1, 0
	s_and_b64 vcc, exec, s[16:17]
	s_cbranch_vccnz .LBB0_253
	s_add_i32 s19, s19, 2
	s_ashr_i32 s19, s19, 2
	v_mad_i64_i32 v[28:29], s[22:23], s19, v230, v[104:105]
	s_add_i32 s22, s14, s18
	s_ashr_i32 s23, s22, 31
	v_lshl_add_u64 v[60:61], s[22:23], 1, v[106:107]
	v_add_co_u32_e32 v40, vcc, 0x20000, v60
	s_and_b32 s19, s18, 64
	s_nop 0
	v_addc_co_u32_e32 v41, vcc, 0, v61, vcc
	v_add_co_u32_e32 v44, vcc, 0x40000, v60
	s_lshl_b32 s84, s19, 1
	s_nop 0
	v_addc_co_u32_e32 v45, vcc, 0, v61, vcc
	v_add_co_u32_e32 v48, vcc, 0x60000, v60
	v_lshl_add_u64 v[28:29], v[28:29], 0, s[84:85]
	s_nop 0
	v_addc_co_u32_e32 v49, vcc, 0, v61, vcc
	v_add_co_u32_e32 v52, vcc, 0x80000, v60
	global_load_dwordx4 v[28:31], v[28:29], off
	s_nop 0
	v_addc_co_u32_e32 v53, vcc, 0, v61, vcc
	v_add_co_u32_e32 v56, vcc, 0xa0000, v60
	global_load_dwordx4 v[36:39], v[60:61], off
	s_nop 0
	global_load_dwordx4 v[40:43], v[40:41], off
	v_addc_co_u32_e32 v57, vcc, 0, v61, vcc
	v_add_co_u32_e32 v62, vcc, 0xc0000, v60
	global_load_dwordx4 v[44:47], v[44:45], off
	s_nop 0
	global_load_dwordx4 v[48:51], v[48:49], off
	v_addc_co_u32_e32 v63, vcc, 0, v61, vcc
	v_add_co_u32_e32 v64, vcc, 0xe0000, v60
	global_load_dwordx4 v[52:55], v[52:53], off
	s_nop 0
	global_load_dwordx4 v[56:59], v[56:57], off
	v_addc_co_u32_e32 v65, vcc, 0, v61, vcc
	global_load_dwordx4 v[60:63], v[62:63], off
	s_nop 0
	global_load_dwordx4 v[64:67], v[64:65], off
	s_add_i32 s20, s20, 2
	s_waitcnt vmcnt(16)
	v_mfma_f32_16x16x32_bf16 v[0:3], v[68:71], v[72:75], v[0:3]
	s_waitcnt vmcnt(15)
	v_mfma_f32_16x16x32_bf16 v[4:7], v[68:71], v[76:79], v[4:7]
	s_waitcnt vmcnt(14)
	v_mfma_f32_16x16x32_bf16 v[8:11], v[68:71], v[80:83], v[8:11]
	s_waitcnt vmcnt(13)
	v_mfma_f32_16x16x32_bf16 v[12:15], v[68:71], v[84:87], v[12:15]
	s_waitcnt vmcnt(12)
	v_mfma_f32_16x16x32_bf16 v[16:19], v[68:71], v[88:91], v[16:19]
	s_waitcnt vmcnt(11)
	v_mfma_f32_16x16x32_bf16 v[20:23], v[68:71], v[92:95], v[20:23]
	s_waitcnt vmcnt(10)
	v_mfma_f32_16x16x32_bf16 v[24:27], v[68:71], v[96:99], v[24:27]
	s_waitcnt vmcnt(9)
	v_mfma_f32_16x16x32_bf16 v[32:35], v[68:71], v[100:103], v[32:35]
	s_add_i32 s18, s18, 64
	s_andn2_b64 vcc, exec, s[16:17]
	v_lshl_add_u64 v[110:111], v[110:111], 0, s[46:47]
	s_cbranch_vccnz .LBB0_254

; #define LAS __attribute__((address_space(3)))
; DI unsigned char* WSP(const Params& p) { GAS unsigned char* w = (GAS unsigned char*)p.ws; asm volatile("" : "+s"(w)); return (unsigned char*)w; }
; DI float bflo(unsigned v) { return __uint_as_float(v << 16); }
; DI float bfhi(unsigned v) { return __uint_as_float(v & 0xffff0000u); }
; DI void pool_item(const Params& p, int L, int item, LAS unsigned char* lds, int tid) {
;     const int gi = item & 3, tile = item >> 2, w = 2 << gi;
;     const int wv = __builtin_amdgcn_readfirstlane(tid >> 6), lane = tid & 63, i16 = lane & 15, quad = lane >> 4;
;     const bf16_t* proj = (const bf16_t*)(WSP(p) + WS_BIG);
;     bf16_t* mix = (bf16_t*)(WSP(p) + WS_XN);
;     LAS bf16_t* dL = (LAS bf16_t*)lds;
;     LAS bf16_t* WT = dL + 64 * 136;
;     {
;         const int tl = tid >> 3, c0 = (tid & 7) * 16, row = tile * 64 + tl, t = row & (T - 1);
;         float sum[16], cur[16];
; #pragma unroll
;         for (int e = 0; e < 16; ++e) { sum[e] = 0.f; cur[e] = 0.f; }
;         const int cnt = (t + 1 < w) ? (t + 1) : w;
;         const bf16_t* src0 = proj + (size_t)row * NINP + C_PV + gi * 128 + c0;
; #pragma unroll 1
;         for (int k0 = 0; k0 < cnt; k0 += 4) {
;             u32x4 v0[4], v1[4];
; #pragma unroll
;             for (int kk = 0; kk < 4; ++kk) { const int k = (k0 + kk < cnt) ? (k0 + kk) : 0;
;                 const bf16_t* src = src0 - (size_t)k * NINP; v0[kk] = *(const u32x4*)src; v1[kk] = *(const u32x4*)(src + 8); }
; #pragma unroll
;             for (int kk = 0; kk < 4; ++kk) { const float wgt = (k0 + kk < cnt) ? 1.f : 0.f;
;                 const float x[16] = {bflo(v0[kk].x), bfhi(v0[kk].x), bflo(v0[kk].y), bfhi(v0[kk].y), bflo(v0[kk].z), bfhi(v0[kk].z), bflo(v0[kk].w), bfhi(v0[kk].w),
;                                      bflo(v1[kk].x), bfhi(v1[kk].x), bflo(v1[kk].y), bfhi(v1[kk].y), bflo(v1[kk].z), bfhi(v1[kk].z), bflo(v1[kk].w), bfhi(v1[kk].w)};
; #pragma unroll
;                 for (int e = 0; e < 16; ++e) { sum[e] += wgt * x[e]; if (k0 + kk == 0) cur[e] = x[e]; } }
.LBB0_287:
	v_readlane_b32 s100, v254, 38
	s_nop 0
	s_add_i32 s100, s100, s2
	s_and_b32 s100, s100, 3
	s_lshl_b32 s101, s100, 7
	s_mov_b32 s20, s101
	s_lshl_b32 s14, s52, 2
	s_or_b32 s14, s14, s100
	s_lshl_b32 s14, s14, 15
	s_mov_b32 s15, 0
	s_lshl_b32 s4, s2, 8
	s_add_i32 s4, s4, s88
	v_mbcnt_lo_u32_b32 v43, -1, 0
	v_mbcnt_hi_u32_b32 v43, -1, v43
	s_lshl_b32 s5, s4, 4
	v_add_u32_e32 v45, s33, v43
	v_ashrrev_i32_e32 v63, 3, v45
	s_andn2_b32 s5, s5, 63
	v_lshlrev_b32_e32 v0, 4, v43
	v_add_u32_e32 v2, s5, v63
	v_and_b32_e32 v3, 0x70, v0
	v_and_b32_e32 v0, 0xfff, v2
	s_mov_b64 s[6:7], s[28:29]
	v_add_u32_e32 v0, 1, v0
	s_lshl_b32 s5, 2, s100
	s_lshl_b32 s84, s20, 1
	v_lshlrev_b32_e32 v198, 1, v3
	v_min_u32_e32 v65, s5, v0
	v_mov_b64_e32 v[0:1], s[6:7]
	v_mad_i64_i32 v[0:1], s[6:7], v2, s96, v[0:1]
	v_lshl_add_u64 v[0:1], v[0:1], 0, s[84:85]
	v_lshl_add_u64 v[0:1], v[0:1], 0, v[198:199]
	s_mov_b64 s[6:7], 0x1be02040
	v_mov_b32_e32 v50, 0
	s_mov_b64 s[18:19], s[28:29]
	v_lshl_add_u64 v[40:41], v[0:1], 0, s[6:7]
	s_mov_b64 s[20:21], 0
	s_mov_b32 s5, 0
	v_mov_b32_e32 v51, v50
	v_mov_b32_e32 v24, v50
	v_mov_b32_e32 v25, v50
	v_mov_b32_e32 v54, v50
	v_mov_b32_e32 v55, v50
	v_mov_b32_e32 v26, v50
	v_mov_b32_e32 v27, v50
	v_mov_b32_e32 v58, v50
	v_mov_b32_e32 v59, v50
	v_mov_b32_e32 v28, v50
	v_mov_b32_e32 v29, v50
	v_mov_b32_e32 v60, v50
	v_mov_b32_e32 v61, v50
	v_mov_b32_e32 v32, v50
	v_mov_b32_e32 v33, v50
	v_mov_b32_e32 v46, v50
	v_mov_b32_e32 v47, v50
	v_mov_b32_e32 v30, v50
	v_mov_b32_e32 v31, v50
	v_mov_b32_e32 v48, v50
	v_mov_b32_e32 v49, v50
	v_mov_b32_e32 v34, v50
	v_mov_b32_e32 v35, v50
	v_mov_b32_e32 v52, v50
	v_mov_b32_e32 v53, v50
	v_mov_b32_e32 v36, v50
	v_mov_b32_e32 v37, v50
	v_mov_b32_e32 v56, v50
	v_mov_b32_e32 v57, v50
	v_mov_b32_e32 v38, v50
	v_mov_b32_e32 v39, v50
.LBB0_288:
	v_mov_b32_e32 v0, s5
	v_cmp_lt_u32_e32 vcc, s5, v65
	s_add_i32 s6, s5, 1
	s_add_i32 s8, s5, 2
	v_cndmask_b32_e32 v2, 0, v0, vcc
	v_mad_u64_u32 v[0:1], s[22:23], v2, s41, v[40:41]
	s_add_i32 s10, s5, 3
	v_mov_b32_e32 v3, s6
	v_cmp_lt_u32_e64 s[6:7], s6, v65
	v_mov_b32_e32 v4, s8
	v_cmp_lt_u32_e64 s[8:9], s8, v65
	v_sub_u32_e32 v1, v1, v2
	v_mov_b32_e32 v5, s10
	v_cmp_lt_u32_e64 s[10:11], s10, v65
	v_cndmask_b32_e64 v6, 0, v3, s[6:7]
	v_cndmask_b32_e64 v7, 0, v4, s[8:9]
	global_load_dwordx4 v[66:69], v[0:1], off
	global_load_dwordx4 v[70:73], v[0:1], off offset:16
	v_cndmask_b32_e64 v8, 0, v5, s[10:11]
	v_cndmask_b32_e64 v62, 0, 1.0, s[6:7]
	v_mad_u64_u32 v[2:3], s[6:7], v6, s41, v[40:41]
	v_mad_u64_u32 v[4:5], s[6:7], v7, s41, v[40:41]
	v_mad_u64_u32 v[74:75], s[6:7], v8, s41, v[40:41]
	v_sub_u32_e32 v3, v3, v6
	v_sub_u32_e32 v5, v5, v7
	v_sub_u32_e32 v75, v75, v8
	global_load_dwordx4 v[20:23], v[2:3], off
	global_load_dwordx4 v[16:19], v[4:5], off
	global_load_dwordx4 v[12:15], v[74:75], off
	global_load_dwordx4 v[8:11], v[2:3], off offset:16
	s_nop 0
	global_load_dwordx4 v[4:7], v[4:5], off offset:16
	s_nop 0
	global_load_dwordx4 v[0:3], v[74:75], off offset:16
	s_cmp_eq_u32 s5, 0
	v_cndmask_b32_e64 v64, 0, 1.0, vcc
	s_cselect_b64 vcc, -1, 0
	v_cndmask_b32_e64 v44, 0, 1.0, s[8:9]
	s_add_i32 s5, s5, 4
	v_cndmask_b32_e64 v42, 0, 1.0, s[10:11]
	s_waitcnt vmcnt(7)
	v_and_b32_e32 v75, 0xffff0000, v66
	v_lshlrev_b32_e32 v74, 16, v66
	v_lshlrev_b32_e32 v76, 16, v67
	v_and_b32_e32 v77, 0xffff0000, v67
	v_lshlrev_b32_e32 v78, 16, v68
	v_and_b32_e32 v79, 0xffff0000, v68
	v_lshlrev_b32_e32 v80, 16, v69
	v_and_b32_e32 v81, 0xffff0000, v69
	s_waitcnt vmcnt(6)
	v_lshlrev_b32_e32 v82, 16, v70
	v_and_b32_e32 v83, 0xffff0000, v70
	v_lshlrev_b32_e32 v84, 16, v71
	v_and_b32_e32 v85, 0xffff0000, v71
	v_lshlrev_b32_e32 v70, 16, v72
	v_and_b32_e32 v71, 0xffff0000, v72
	v_lshlrev_b32_e32 v68, 16, v73
	v_and_b32_e32 v69, 0xffff0000, v73
	v_pk_fma_f32 v[72:73], v[64:65], v[74:75], v[60:61] op_sel_hi:[0,1,1]
	v_cndmask_b32_e32 v33, v33, v75, vcc
	v_cndmask_b32_e32 v32, v32, v74, vcc
	s_waitcnt vmcnt(5)
	v_lshlrev_b32_e32 v74, 16, v20
	v_and_b32_e32 v75, 0xffff0000, v20
	v_pk_fma_f32 v[58:59], v[64:65], v[76:77], v[58:59] op_sel_hi:[0,1,1]
	v_cndmask_b32_e32 v29, v29, v77, vcc
	v_cndmask_b32_e32 v28, v28, v76, vcc
	v_lshlrev_b32_e32 v76, 16, v21
	v_and_b32_e32 v77, 0xffff0000, v21
	v_pk_fma_f32 v[54:55], v[64:65], v[78:79], v[54:55] op_sel_hi:[0,1,1]
	v_cndmask_b32_e32 v27, v27, v79, vcc
	v_cndmask_b32_e32 v26, v26, v78, vcc
	v_lshlrev_b32_e32 v78, 16, v22
	v_and_b32_e32 v79, 0xffff0000, v22
	v_pk_fma_f32 v[50:51], v[64:65], v[80:81], v[50:51] op_sel_hi:[0,1,1]
	v_cndmask_b32_e32 v25, v25, v81, vcc
	v_cndmask_b32_e32 v24, v24, v80, vcc
	v_lshlrev_b32_e32 v22, 16, v23
	v_and_b32_e32 v23, 0xffff0000, v23
	v_pk_fma_f32 v[56:57], v[64:65], v[82:83], v[56:57] op_sel_hi:[0,1,1]
	s_waitcnt vmcnt(2)
	v_lshlrev_b32_e32 v80, 16, v8
	v_and_b32_e32 v81, 0xffff0000, v8
	v_pk_fma_f32 v[52:53], v[64:65], v[84:85], v[52:53] op_sel_hi:[0,1,1]
	v_lshlrev_b32_e32 v8, 16, v9
	v_and_b32_e32 v9, 0xffff0000, v9
	v_pk_fma_f32 v[48:49], v[64:65], v[70:71], v[48:49] op_sel_hi:[0,1,1]
	v_cndmask_b32_e32 v35, v35, v71, vcc
	v_cndmask_b32_e32 v34, v34, v70, vcc
	v_lshlrev_b32_e32 v70, 16, v10
	v_and_b32_e32 v71, 0xffff0000, v10
	v_pk_fma_f32 v[46:47], v[64:65], v[68:69], v[46:47] op_sel_hi:[0,1,1]
	v_lshlrev_b32_e32 v10, 16, v11
	v_and_b32_e32 v11, 0xffff0000, v11
	v_lshlrev_b32_e32 v66, 16, v16
	v_and_b32_e32 v67, 0xffff0000, v16
	v_lshlrev_b32_e32 v16, 16, v17
	v_and_b32_e32 v17, 0xffff0000, v17
	v_lshlrev_b32_e32 v86, 16, v18
	v_and_b32_e32 v87, 0xffff0000, v18
	v_lshlrev_b32_e32 v18, 16, v19
	v_and_b32_e32 v19, 0xffff0000, v19
	v_cndmask_b32_e32 v39, v39, v83, vcc
	v_cndmask_b32_e32 v38, v38, v82, vcc
	s_waitcnt vmcnt(1)
; #define LAS __attribute__((address_space(3)))
; DI unsigned char* WSP(const Params& p) { GAS unsigned char* w = (GAS unsigned char*)p.ws; asm volatile("" : "+s"(w)); return (unsigned char*)w; }
; DI unsigned pk2(float lo, float hi) { f32x2 v = {lo, hi}; bf16v2 b = __builtin_convertvector(v, bf16v2); return __builtin_bit_cast(unsigned, b); }
; DI float bflo(unsigned v) { return __uint_as_float(v << 16); }
; DI float bfhi(unsigned v) { return __uint_as_float(v & 0xffff0000u); }
; DI void pool_item(const Params& p, int L, int item, LAS unsigned char* lds, int tid) {
;     ...
;             for (int kk = 0; kk < 4; ++kk) { const float wgt = (k0 + kk < cnt) ? 1.f : 0.f;
;                 const float x[16] = {bflo(v0[kk].x), bfhi(v0[kk].x), bflo(v0[kk].y), bfhi(v0[kk].y), bflo(v0[kk].z), bfhi(v0[kk].z), bflo(v0[kk].w), bfhi(v0[kk].w),
;                                      bflo(v1[kk].x), bfhi(v1[kk].x), bflo(v1[kk].y), bfhi(v1[kk].y), bflo(v1[kk].z), bfhi(v1[kk].z), bflo(v1[kk].w), bfhi(v1[kk].w)};
; #pragma unroll
;                 for (int e = 0; e < 16; ++e) { sum[e] += wgt * x[e]; if (k0 + kk == 0) cur[e] = x[e]; } }
;         }
;         const float inv = 1.f / (float)cnt;
;         float dv[16];
; #pragma unroll
;         for (int e = 0; e < 16; ++e) dv[e] = sum[e] * inv - cur[e];
;         *(LAS u32x4*)(dL + tl * 136 + c0) = (u32x4){pk2(dv[0], dv[1]), pk2(dv[2], dv[3]), pk2(dv[4], dv[5]), pk2(dv[6], dv[7])};
;         *(LAS u32x4*)(dL + tl * 136 + c0 + 8) = (u32x4){pk2(dv[8], dv[9]), pk2(dv[10], dv[11]), pk2(dv[12], dv[13]), pk2(dv[14], dv[15])};
;         const bf16_t* pwt = (const bf16_t*)(WSP(p) + WS_PWT) + (size_t)(L * 4 + gi) * 16384;
;         u32x4 wreg[4];
; #pragma unroll
;         for (int i = 0; i < 4; ++i) { const int q = tid + 512 * i, o = q >> 4, cc = (q & 15) * 8; wreg[i] = *(const u32x4*)(pwt + o * 128 + cc); }
;         __builtin_amdgcn_sched_barrier(0);
; #pragma unroll
;         for (int i = 0; i < 4; ++i) { const int q = tid + 512 * i, o = q >> 4, cc = (q & 15) * 8; *(LAS u32x4*)(WT + o * 136 + cc) = wreg[i]; }
;     }
;     __syncthreads();
	v_lshlrev_b32_e32 v82, 16, v4
	v_and_b32_e32 v83, 0xffff0000, v4
	v_cndmask_b32_e32 v37, v37, v85, vcc
	v_cndmask_b32_e32 v36, v36, v84, vcc
	v_lshlrev_b32_e32 v4, 16, v5
	v_and_b32_e32 v5, 0xffff0000, v5
	v_lshlrev_b32_e32 v84, 16, v6
	v_and_b32_e32 v85, 0xffff0000, v6
	v_cndmask_b32_e32 v31, v31, v69, vcc
	v_cndmask_b32_e32 v30, v30, v68, vcc
	v_lshlrev_b32_e32 v6, 16, v7
	v_and_b32_e32 v7, 0xffff0000, v7
	v_pk_fma_f32 v[68:69], v[62:63], v[74:75], v[72:73] op_sel_hi:[0,1,1]
	v_pk_fma_f32 v[58:59], v[62:63], v[76:77], v[58:59] op_sel_hi:[0,1,1]
	v_pk_fma_f32 v[54:55], v[62:63], v[78:79], v[54:55] op_sel_hi:[0,1,1]
	v_pk_fma_f32 v[22:23], v[62:63], v[22:23], v[50:51] op_sel_hi:[0,1,1]
	v_pk_fma_f32 v[50:51], v[62:63], v[80:81], v[56:57] op_sel_hi:[0,1,1]
	v_pk_fma_f32 v[8:9], v[62:63], v[8:9], v[52:53] op_sel_hi:[0,1,1]
	v_pk_fma_f32 v[48:49], v[62:63], v[70:71], v[48:49] op_sel_hi:[0,1,1]
	v_pk_fma_f32 v[10:11], v[62:63], v[10:11], v[46:47] op_sel_hi:[0,1,1]
	v_lshlrev_b32_e32 v60, 16, v12
	v_and_b32_e32 v61, 0xffff0000, v12
	v_lshlrev_b32_e32 v12, 16, v13
	v_and_b32_e32 v13, 0xffff0000, v13
	v_lshlrev_b32_e32 v20, 16, v14
	v_and_b32_e32 v21, 0xffff0000, v14
	v_lshlrev_b32_e32 v14, 16, v15
	v_and_b32_e32 v15, 0xffff0000, v15
	s_waitcnt vmcnt(0)
	v_lshlrev_b32_e32 v88, 16, v0
	v_and_b32_e32 v89, 0xffff0000, v0
	v_lshlrev_b32_e32 v0, 16, v1
	v_and_b32_e32 v1, 0xffff0000, v1
	v_lshlrev_b32_e32 v90, 16, v2
	v_and_b32_e32 v91, 0xffff0000, v2
	v_lshlrev_b32_e32 v2, 16, v3
	v_and_b32_e32 v3, 0xffff0000, v3
	v_cmp_ge_u32_e32 vcc, s5, v65
	v_pk_fma_f32 v[46:47], v[44:45], v[66:67], v[68:69] op_sel_hi:[0,1,1]
	v_pk_fma_f32 v[16:17], v[44:45], v[16:17], v[58:59] op_sel_hi:[0,1,1]
	v_pk_fma_f32 v[52:53], v[44:45], v[86:87], v[54:55] op_sel_hi:[0,1,1]
	v_pk_fma_f32 v[18:19], v[44:45], v[18:19], v[22:23] op_sel_hi:[0,1,1]
	v_pk_fma_f32 v[22:23], v[44:45], v[82:83], v[50:51] op_sel_hi:[0,1,1]
	v_pk_fma_f32 v[4:5], v[44:45], v[4:5], v[8:9] op_sel_hi:[0,1,1]
	v_pk_fma_f32 v[8:9], v[44:45], v[84:85], v[48:49] op_sel_hi:[0,1,1]
	v_pk_fma_f32 v[6:7], v[44:45], v[6:7], v[10:11] op_sel_hi:[0,1,1]
	s_or_b64 s[20:21], vcc, s[20:21]
	v_pk_fma_f32 v[60:61], v[42:43], v[60:61], v[46:47] op_sel_hi:[0,1,1]
	v_pk_fma_f32 v[58:59], v[42:43], v[12:13], v[16:17] op_sel_hi:[0,1,1]
	v_pk_fma_f32 v[54:55], v[42:43], v[20:21], v[52:53] op_sel_hi:[0,1,1]
	v_pk_fma_f32 v[50:51], v[42:43], v[14:15], v[18:19] op_sel_hi:[0,1,1]
	v_pk_fma_f32 v[56:57], v[42:43], v[88:89], v[22:23] op_sel_hi:[0,1,1]
	v_pk_fma_f32 v[52:53], v[42:43], v[0:1], v[4:5] op_sel_hi:[0,1,1]
	v_pk_fma_f32 v[48:49], v[42:43], v[90:91], v[8:9] op_sel_hi:[0,1,1]
	v_pk_fma_f32 v[46:47], v[42:43], v[2:3], v[6:7] op_sel_hi:[0,1,1]
	s_andn2_b64 exec, exec, s[20:21]
	s_cbranch_execnz .LBB0_288
	s_or_b64 exec, exec, s[20:21]
	v_cvt_f32_ubyte0_e32 v0, v65
	v_div_scale_f32 v1, s[6:7], v0, v0, 1.0
	v_rcp_f32_e32 v2, v1
	v_div_scale_f32 v3, vcc, 1.0, v0, 1.0
	s_mov_b64 s[6:7], s[28:29]
	v_fma_f32 v4, -v1, v2, 1.0
	v_fmac_f32_e32 v2, v4, v2
	v_mul_f32_e32 v4, v3, v2
	v_fma_f32 v5, -v1, v4, v3
	v_fmac_f32_e32 v4, v5, v2
	v_fma_f32 v1, -v1, v4, v3
	v_div_fmas_f32 v1, v1, v2, v4
	v_div_fixup_f32 v0, v1, v0, 1.0
	v_pk_fma_f32 v[4:5], v[0:1], v[58:59], v[28:29] op_sel_hi:[0,1,1] neg_lo:[0,0,1] neg_hi:[0,0,1]
	v_pk_fma_f32 v[2:3], v[0:1], v[60:61], v[32:33] op_sel_hi:[0,1,1] neg_lo:[0,0,1] neg_hi:[0,0,1]
	v_pk_fma_f32 v[6:7], v[0:1], v[54:55], v[26:27] op_sel_hi:[0,1,1] neg_lo:[0,0,1] neg_hi:[0,0,1]
	v_pk_fma_f32 v[8:9], v[0:1], v[50:51], v[24:25] op_sel_hi:[0,1,1] neg_lo:[0,0,1] neg_hi:[0,0,1]
	v_pk_fma_f32 v[10:11], v[0:1], v[56:57], v[38:39] op_sel_hi:[0,1,1] neg_lo:[0,0,1] neg_hi:[0,0,1]
	v_pk_fma_f32 v[12:13], v[0:1], v[52:53], v[36:37] op_sel_hi:[0,1,1] neg_lo:[0,0,1] neg_hi:[0,0,1]
	v_pk_fma_f32 v[14:15], v[0:1], v[48:49], v[34:35] op_sel_hi:[0,1,1] neg_lo:[0,0,1] neg_hi:[0,0,1]
	v_pk_fma_f32 v[16:17], v[0:1], v[46:47], v[30:31] op_sel_hi:[0,1,1] neg_lo:[0,0,1] neg_hi:[0,0,1]
	v_cvt_pk_bf16_f32 v1, v4, v5
	v_mul_lo_u32 v4, v63, s68
	v_cvt_pk_bf16_f32 v0, v2, v3
	v_cvt_pk_bf16_f32 v2, v6, v7
	v_cvt_pk_bf16_f32 v3, v8, v9
	v_add3_u32 v4, 0, v4, v198
	ds_write_b128 v4, v[0:3]
	v_cvt_pk_bf16_f32 v0, v10, v11
	v_cvt_pk_bf16_f32 v1, v12, v13
	v_cvt_pk_bf16_f32 v2, v14, v15
	v_cvt_pk_bf16_f32 v3, v16, v17
	ds_write_b128 v4, v[0:3] offset:16
	s_add_u32 s6, s6, s14
	v_lshlrev_b32_e32 v0, 4, v45
	s_addc_u32 s7, s7, s15
	v_lshlrev_b32_e32 v2, 3, v45
	v_and_b32_e32 v198, 0xf0, v0
	v_lshl_add_u64 v[0:1], s[6:7], 0, v[198:199]
	s_mov_b64 s[6:7], 0x3a6a3000
	v_and_b32_e32 v10, 0xffffff80, v2
	v_lshl_add_u64 v[8:9], v[0:1], 0, s[6:7]
	v_ashrrev_i32_e32 v11, 31, v10
	v_lshl_add_u64 v[0:1], v[10:11], 1, v[8:9]
	v_add_u32_e32 v2, 0x1000, v10
	v_add_u32_e32 v12, 0x2000, v10
	v_add_u32_e32 v10, 0x3000, v10
	v_ashrrev_i32_e32 v3, 31, v2
	v_ashrrev_i32_e32 v13, 31, v12
	v_ashrrev_i32_e32 v11, 31, v10
	v_lshl_add_u64 v[4:5], v[2:3], 1, v[8:9]
	v_lshl_add_u64 v[12:13], v[12:13], 1, v[8:9]
	v_lshl_add_u64 v[14:15], v[10:11], 1, v[8:9]
	global_load_dwordx4 v[0:3], v[0:1], off
	s_nop 0
	global_load_dwordx4 v[4:7], v[4:5], off
	s_nop 0
	global_load_dwordx4 v[8:11], v[12:13], off
	s_nop 0
	global_load_dwordx4 v[12:15], v[14:15], off
	v_readfirstlane_b32 s8, v45
	v_and_b32_e32 v17, 15, v43
	v_add_u32_e32 v16, 0, v198
	v_lshrrev_b32_e32 v18, 4, v45
	v_mad_u64_u32 v[18:19], s[6:7], v18, s68, v[16:17]
	s_waitcnt vmcnt(3)
	ds_write_b128 v18, v[0:3] offset:17408
	v_add_u32_e32 v0, 0x200, v45
	v_lshrrev_b32_e32 v0, 4, v0
	v_mad_u64_u32 v[0:1], s[6:7], v0, s68, v[16:17]
	s_waitcnt vmcnt(2)
	ds_write_b128 v0, v[4:7] offset:17408
	v_add_u32_e32 v0, 0x400, v45
	v_lshrrev_b32_e32 v0, 4, v0
	v_mad_u64_u32 v[0:1], s[6:7], v0, s68, v[16:17]
	s_waitcnt vmcnt(1)
	ds_write_b128 v0, v[8:11] offset:17408
	v_add_u32_e32 v0, 0x600, v45
	v_lshrrev_b32_e32 v0, 4, v0
	v_bfe_u32 v18, v43, 4, 2
	v_mad_u64_u32 v[0:1], s[6:7], v0, s68, v[16:17]
	s_bfe_u32 s5, s8, 0x20006
	v_lshlrev_b32_e32 v30, 4, v18
	s_and_b32 s4, s4, 0xffffffc
	s_waitcnt vmcnt(0)
	ds_write_b128 v0, v[12:15] offset:17408
	v_lshl_or_b32 v0, s5, 4, v17
	v_add_u32_e32 v16, 0, v30
	s_or_b32 s4, s5, s4
	v_mad_u32_u24 v0, v0, s68, v16
	v_lshl_or_b32 v34, s4, 4, v17
	s_mov_b32 s4, 22
	s_waitcnt lgkmcnt(0)
	s_barrier
; #define LAS __attribute__((address_space(3)))
; DI f32x4 zero4() { float a, b, c, d; asm volatile("v_mov_b32 %0, 0\n\tv_mov_b32 %1, 0\n\tv_mov_b32 %2, 0\n\tv_mov_b32 %3, 0\n\ts_nop 1" : "=v"(a), "=v"(b), "=v"(c), "=v"(d)); return (f32x4){a, b, c, d}; }
; DI const float* INP(const Params& p, int i) { asm volatile("" : "+s"(i)); return (const float*)(GAS const float*)p.in[i]; }
; DI unsigned pk2(float lo, float hi) { f32x2 v = {lo, hi}; bf16v2 b = __builtin_convertvector(v, bf16v2); return __builtin_bit_cast(unsigned, b); }
; DI void pool_item(const Params& p, int L, int item, LAS unsigned char* lds, int tid) {
;     ...
;     const int ttile = wv & 3, ot0 = (wv >> 2) * 4;
;     bf16x8 df[4];
; #pragma unroll
;     for (int kk = 0; kk < 4; ++kk) df[kk] = *(const LAS bf16x8*)(dL + (ttile * 16 + i16) * 136 + kk * 32 + quad * 8);
;     const size_t trow = (size_t)(tile * 64 + ttile * 16 + i16);
;     f32x4 scv[4];
; #pragma unroll
;     for (int j = 0; j < 4; ++j) scv[j] = *(const f32x4*)(INP(p, 22) + L * 512 + gi * 128 + (ot0 + j) * 16 + quad * 4);
; #pragma unroll
;     for (int j = 0; j < 4; ++j) { f32x4 acc = zero4();
; #pragma unroll
;         for (int kk = 0; kk < 4; ++kk) { const bf16x8 wf = *(const LAS bf16x8*)(WT + ((ot0 + j) * 16 + i16) * 136 + kk * 32 + quad * 8);
;             acc = __builtin_amdgcn_mfma_f32_16x16x32_bf16(wf, df[kk], acc, 0, 0, 0); }
;         const int o4 = (ot0 + j) * 16 + quad * 4;
;         const f32x4 sc = scv[j];
;         u32x2 ov; ov.x = pk2(acc[0] * sc.x, acc[1] * sc.y); ov.y = pk2(acc[2] * sc.z, acc[3] * sc.w);
;         *(u32x2*)(mix + trow * D + 1536 + gi * 128 + o4) = ov; }
;     __syncthreads();
	ds_read_b128 v[12:15], v0
	ds_read_b128 v[8:11], v0 offset:64
	ds_read_b128 v[4:7], v0 offset:128
	ds_read_b128 v[0:3], v0 offset:192
	s_ashr_i32 s5, s4, 31
	s_lshl_b64 s[4:5], s[4:5], 3
	s_add_u32 s4, s0, s4
	s_addc_u32 s5, s1, s5
	s_load_dwordx2 s[4:5], s[4:5], 0x0
	s_mov_b32 s20, s101
	v_lshlrev_b32_e32 v46, 2, v18
	v_ashrrev_i32_e32 v35, 31, v34
	v_lshlrev_b64 v[34:35], 12, v[34:35]
	s_waitcnt lgkmcnt(0)
	s_add_u32 s4, s4, s16
	s_addc_u32 s5, s5, s17
	s_lshl_b32 s10, s20, 2
	s_add_u32 s9, s4, s10
	s_addc_u32 s11, s5, 0
	s_ashr_i32 s4, s8, 2
	s_and_b32 s6, s4, 0xffffffc0
	s_ashr_i32 s7, s6, 31
	s_lshl_b64 s[4:5], s[6:7], 2
	s_add_u32 s8, s9, s4
	s_addc_u32 s9, s11, s5
	global_load_dwordx4 v[18:21], v30, s[8:9]
	s_mov_b32 s8, 22
	s_ashr_i32 s9, s8, 31
	s_lshl_b64 s[8:9], s[8:9], 3
	s_add_u32 s8, s0, s8
	s_addc_u32 s9, s1, s9
	s_load_dwordx2 s[8:9], s[8:9], 0x0
	v_lshl_add_u64 v[34:35], s[18:19], 0, v[34:35]
	v_lshl_add_u64 v[34:35], v[34:35], 0, s[84:85]
	v_or_b32_e32 v17, s6, v17
	s_waitcnt lgkmcnt(0)
	s_add_u32 s8, s8, s16
	s_addc_u32 s9, s9, s17
	s_add_u32 s8, s8, s10
	s_addc_u32 s9, s9, 0
	s_add_u32 s8, s8, s4
	s_addc_u32 s9, s9, s5
	global_load_dwordx4 v[22:25], v30, s[8:9] offset:64
	s_mov_b32 s8, 22
	s_ashr_i32 s9, s8, 31
	s_lshl_b64 s[8:9], s[8:9], 3
	s_add_u32 s8, s0, s8
	s_addc_u32 s9, s1, s9
	s_load_dwordx2 s[8:9], s[8:9], 0x0
	s_waitcnt lgkmcnt(0)
	s_add_u32 s8, s8, s16
	s_addc_u32 s9, s9, s17
	s_add_u32 s8, s8, s10
	s_addc_u32 s9, s9, 0
	s_add_u32 s8, s8, s4
	s_addc_u32 s9, s9, s5
	global_load_dwordx4 v[26:29], v30, s[8:9] offset:128
	s_mov_b32 s8, 22
	s_ashr_i32 s9, s8, 31
	s_lshl_b64 s[8:9], s[8:9], 3
	s_add_u32 s8, s0, s8
	s_addc_u32 s9, s1, s9
	s_load_dwordx2 s[8:9], s[8:9], 0x0
	s_waitcnt lgkmcnt(0)
	s_add_u32 s8, s8, s16
	s_addc_u32 s9, s9, s17
	s_add_u32 s8, s8, s10
	s_addc_u32 s9, s9, 0
	s_add_u32 s4, s8, s4
	s_addc_u32 s5, s9, s5
	global_load_dwordx4 v[30:33], v30, s[4:5] offset:192
	s_mov_b64 s[4:5], 0x13e00c00
	v_lshl_add_u64 v[42:43], v[34:35], 0, s[4:5]
	v_mad_u64_u32 v[44:45], s[4:5], v17, s68, v[16:17]
	v_mov_b32 v34, 0
	v_mov_b32 v35, 0
	v_mov_b32 v36, 0
	v_mov_b32 v37, 0
	s_nop 1
	ds_read_b128 v[38:41], v44 offset:17408
	s_waitcnt lgkmcnt(0)
	v_mfma_f32_16x16x32_bf16 v[34:37], v[38:41], v[12:15], v[34:37]
	ds_read_b128 v[38:41], v44 offset:17472
	s_add_i32 s2, s2, 1
	s_cmp_lg_u32 s2, 8
	s_waitcnt lgkmcnt(0)
	v_mfma_f32_16x16x32_bf16 v[34:37], v[38:41], v[8:11], v[34:37]
	ds_read_b128 v[38:41], v44 offset:17536
	s_waitcnt lgkmcnt(0)
	v_mfma_f32_16x16x32_bf16 v[34:37], v[38:41], v[4:7], v[34:37]
	ds_read_b128 v[38:41], v44 offset:17600
	s_waitcnt lgkmcnt(0)
	v_mfma_f32_16x16x32_bf16 v[34:37], v[38:41], v[0:3], v[34:37]
	v_or_b32_e32 v38, s6, v46
	v_ashrrev_i32_e32 v39, 31, v38
	s_waitcnt vmcnt(3)
	s_nop 4
	v_pk_mul_f32 v[20:21], v[20:21], v[36:37]
	v_pk_mul_f32 v[18:19], v[18:19], v[34:35]
	v_or_b32_e32 v34, 16, v17
	v_cvt_pk_bf16_f32 v18, v18, v19
	v_cvt_pk_bf16_f32 v19, v20, v21
	v_lshl_add_u64 v[20:21], v[38:39], 1, v[42:43]
	v_mad_u64_u32 v[40:41], s[4:5], v34, s68, v[16:17]
	global_store_dwordx2 v[20:21], v[18:19], off
	v_mov_b32 v18, 0
	v_mov_b32 v19, 0
	v_mov_b32 v20, 0
	v_mov_b32 v21, 0
	s_nop 1
	ds_read_b128 v[34:37], v40 offset:17408
	s_waitcnt lgkmcnt(0)
	v_mfma_f32_16x16x32_bf16 v[18:21], v[34:37], v[12:15], v[18:21]
	ds_read_b128 v[34:37], v40 offset:17472
	v_mov_b32_e32 v39, s7
	s_waitcnt lgkmcnt(0)
	v_mfma_f32_16x16x32_bf16 v[18:21], v[34:37], v[8:11], v[18:21]
	ds_read_b128 v[34:37], v40 offset:17536
	s_waitcnt lgkmcnt(0)
	v_mfma_f32_16x16x32_bf16 v[18:21], v[34:37], v[4:7], v[18:21]
	ds_read_b128 v[34:37], v40 offset:17600
	s_waitcnt lgkmcnt(0)
	v_mfma_f32_16x16x32_bf16 v[18:21], v[34:37], v[0:3], v[18:21]
	v_lshl_add_u64 v[34:35], v[38:39], 1, v[42:43]
	s_waitcnt vmcnt(3)
	s_nop 5
	v_pk_mul_f32 v[20:21], v[24:25], v[20:21]
	v_pk_mul_f32 v[18:19], v[22:23], v[18:19]
	v_or_b32_e32 v22, 32, v17
	v_cvt_pk_bf16_f32 v18, v18, v19
	v_cvt_pk_bf16_f32 v19, v20, v21
	v_mad_u64_u32 v[36:37], s[4:5], v22, s68, v[16:17]
	global_store_dwordx2 v[34:35], v[18:19], off offset:32
	v_mov_b32 v18, 0
	v_mov_b32 v19, 0
	v_mov_b32 v20, 0
	v_mov_b32 v21, 0
	s_nop 1
	ds_read_b128 v[22:25], v36 offset:17408
	s_waitcnt lgkmcnt(0)
	v_mfma_f32_16x16x32_bf16 v[18:21], v[22:25], v[12:15], v[18:21]
	ds_read_b128 v[22:25], v36 offset:17472
	v_or_b32_e32 v17, 48, v17
	s_waitcnt lgkmcnt(0)
	v_mfma_f32_16x16x32_bf16 v[18:21], v[22:25], v[8:11], v[18:21]
	ds_read_b128 v[22:25], v36 offset:17536
	s_waitcnt lgkmcnt(0)
	v_mfma_f32_16x16x32_bf16 v[18:21], v[22:25], v[4:7], v[18:21]
	ds_read_b128 v[22:25], v36 offset:17600
	s_waitcnt lgkmcnt(0)
	v_mfma_f32_16x16x32_bf16 v[18:21], v[22:25], v[0:3], v[18:21]
	s_waitcnt vmcnt(3)
	s_nop 6
	v_pk_mul_f32 v[20:21], v[28:29], v[20:21]
	v_pk_mul_f32 v[18:19], v[26:27], v[18:19]
	v_mad_u64_u32 v[26:27], s[4:5], v17, s68, v[16:17]
	v_cvt_pk_bf16_f32 v18, v18, v19
	v_cvt_pk_bf16_f32 v19, v20, v21
	global_store_dwordx2 v[34:35], v[18:19], off offset:64
	v_mov_b32 v18, 0
	v_mov_b32 v19, 0
	v_mov_b32 v20, 0
	v_mov_b32 v21, 0
	s_nop 1
	ds_read_b128 v[22:25], v26 offset:17408
	s_waitcnt lgkmcnt(0)
	v_mfma_f32_16x16x32_bf16 v[12:15], v[22:25], v[12:15], v[18:21]
	s_nop 2
	ds_read_b128 v[16:19], v26 offset:17472
	s_waitcnt lgkmcnt(0)
	v_mfma_f32_16x16x32_bf16 v[8:11], v[16:19], v[8:11], v[12:15]
	s_nop 2
	ds_read_b128 v[12:15], v26 offset:17536
	s_waitcnt lgkmcnt(0)
	v_mfma_f32_16x16x32_bf16 v[4:7], v[12:15], v[4:7], v[8:11]
	s_nop 2
	ds_read_b128 v[8:11], v26 offset:17600
	s_waitcnt lgkmcnt(0)
	v_mfma_f32_16x16x32_bf16 v[0:3], v[8:11], v[0:3], v[4:7]
	s_waitcnt vmcnt(3)
	s_nop 6
	v_pk_mul_f32 v[2:3], v[32:33], v[2:3]
	v_pk_mul_f32 v[0:1], v[30:31], v[0:1]
	s_nop 0
	v_cvt_pk_bf16_f32 v0, v0, v1
	v_cvt_pk_bf16_f32 v1, v2, v3
	global_store_dwordx2 v[34:35], v[0:1], off offset:96
	s_barrier
	s_cbranch_scc1 .LBB0_287
	v_readlane_b32 s18, v254, 58
	s_mov_b32 s2, 0
	v_readlane_b32 s16, v254, 40
	v_readlane_b32 s19, v254, 59
	v_readlane_b32 s17, v254, 51
	v_readlane_b32 s20, v254, 62
	s_mov_b32 s21, 0x3a080000
	s_mov_b32 s22, 0x3a180000
	s_movk_i32 s23, 0x104
	v_readlane_b32 s24, v255, 19
	v_readlane_b32 s54, v255, 17
	s_mov_b64 s[56:57], 0x3a080000
	s_mov_b64 s[62:63], 0x3a180000
	s_mov_b64 s[80:81], 0x35e00000
	v_readlane_b32 s25, v255, 20
	v_readlane_b32 s55, v255, 18

; DI f32x4 zero4() { float a, b, c, d; asm volatile("v_mov_b32 %0, 0\n\tv_mov_b32 %1, 0\n\tv_mov_b32 %2, 0\n\tv_mov_b32 %3, 0\n\ts_nop 1" : "=v"(a), "=v"(b), "=v"(c), "=v"(d)); return (f32x4){a, b, c, d}; }
; DI unsigned pk2(float lo, float hi) { f32x2 v = {lo, hi}; bf16v2 b = __builtin_convertvector(v, bf16v2); return __builtin_bit_cast(unsigned, b); }
; DI void win_tail(const bf16_t* xn, const bf16_t* wint, bf16_t* proj, int bid, int G, int tid) {
;     ...
;     for (int rb = bid; rb < MT / 128; rb += G) {
;         const int r0 = rb * 128 + w * 16;
;         const bf16_t* ap = xn + (size_t)(r0 + i16) * D + quad * 8;
;         const bf16_t* bp = wint + (size_t)(4608 + i16) * D + quad * 8;
;         f32x4 acc0 = zero4(), acc1 = zero4();
; #pragma unroll 8
;         for (int ks = 0; ks < 64; ++ks) {
;             const bf16x8 a = *(const bf16x8*)(ap + ks * 32);
;             const bf16x8 b0 = *(const bf16x8*)(bp + ks * 32), b1 = *(const bf16x8*)(bp + (size_t)16 * D + ks * 32);
;             acc0 = __builtin_amdgcn_mfma_f32_16x16x32_bf16(b0, a, acc0, 0, 0, 0);
;             acc1 = __builtin_amdgcn_mfma_f32_16x16x32_bf16(b1, a, acc1, 0, 0, 0);
;         }
;         bf16_t* op = proj + (size_t)(r0 + i16) * NINP + 4608 + quad * 4;
;         u32x2 o0, o1; o0.x = pk2(acc0[0], acc0[1]); o0.y = pk2(acc0[2], acc0[3]); o1.x = pk2(acc1[0], acc1[1]); o1.y = pk2(acc1[2], acc1[3]);
;         *(u32x2*)op = o0; *(u32x2*)(op + 16) = o1;
;     }
; }
.LBB0_757:
	v_lshl_add_u64 v[16:17], v[14:15], 0, s[4:5]
	v_add_co_u32_e32 v34, vcc, 0x13e00000, v16
	v_lshl_add_u64 v[18:19], v[8:9], 0, s[4:5]
	s_nop 0
	v_addc_co_u32_e32 v35, vcc, 0, v17, vcc
	v_add_co_u32_e32 v16, vcc, 0x5400000, v18
	s_nop 1
	v_addc_co_u32_e32 v17, vcc, 0, v19, vcc
	v_add_co_u32_e32 v18, vcc, 0x5410000, v18
	s_nop 1
	v_addc_co_u32_e32 v19, vcc, 0, v19, vcc
	global_load_dwordx4 v[40:43], v[34:35], off
	global_load_dwordx4 v[44:47], v[16:17], off
	global_load_dwordx4 v[48:51], v[18:19], off
	global_load_dwordx4 v[52:55], v[34:35], off offset:64
	global_load_dwordx4 v[56:59], v[16:17], off offset:64
	global_load_dwordx4 v[60:63], v[18:19], off offset:64
	global_load_dwordx4 v[64:67], v[34:35], off offset:128
	global_load_dwordx4 v[68:71], v[16:17], off offset:128
	global_load_dwordx4 v[72:75], v[18:19], off offset:128
	global_load_dwordx4 v[76:79], v[34:35], off offset:192
	global_load_dwordx4 v[80:83], v[16:17], off offset:192
	global_load_dwordx4 v[84:87], v[18:19], off offset:192
	global_load_dwordx4 v[88:91], v[34:35], off offset:256
	global_load_dwordx4 v[92:95], v[16:17], off offset:256
	global_load_dwordx4 v[96:99], v[18:19], off offset:256
	global_load_dwordx4 v[100:103], v[34:35], off offset:320
	global_load_dwordx4 v[104:107], v[16:17], off offset:320
	global_load_dwordx4 v[108:111], v[18:19], off offset:320
	global_load_dwordx4 v[112:115], v[34:35], off offset:384
	global_load_dwordx4 v[116:119], v[16:17], off offset:384
	global_load_dwordx4 v[120:123], v[18:19], off offset:384
	global_load_dwordx4 v[124:127], v[34:35], off offset:448
	global_load_dwordx4 v[128:131], v[16:17], off offset:448
	global_load_dwordx4 v[132:135], v[18:19], off offset:448
	s_add_u32 s4, s4, 0x200
	s_addc_u32 s5, s5, 0
	s_waitcnt vmcnt(21)
	v_mfma_f32_16x16x32_bf16 v[0:3], v[44:47], v[40:43], v[0:3]
	v_mfma_f32_16x16x32_bf16 v[4:7], v[48:51], v[40:43], v[4:7]
	s_waitcnt vmcnt(18)
	v_mfma_f32_16x16x32_bf16 v[0:3], v[56:59], v[52:55], v[0:3]
	v_mfma_f32_16x16x32_bf16 v[4:7], v[60:63], v[52:55], v[4:7]
	s_waitcnt vmcnt(15)
	v_mfma_f32_16x16x32_bf16 v[0:3], v[68:71], v[64:67], v[0:3]
	v_mfma_f32_16x16x32_bf16 v[4:7], v[72:75], v[64:67], v[4:7]
	s_waitcnt vmcnt(12)
	v_mfma_f32_16x16x32_bf16 v[0:3], v[80:83], v[76:79], v[0:3]
	v_mfma_f32_16x16x32_bf16 v[4:7], v[84:87], v[76:79], v[4:7]
	s_waitcnt vmcnt(9)
	v_mfma_f32_16x16x32_bf16 v[0:3], v[92:95], v[88:91], v[0:3]
	v_mfma_f32_16x16x32_bf16 v[4:7], v[96:99], v[88:91], v[4:7]
	s_waitcnt vmcnt(6)
	v_mfma_f32_16x16x32_bf16 v[0:3], v[104:107], v[100:103], v[0:3]
	v_mfma_f32_16x16x32_bf16 v[4:7], v[108:111], v[100:103], v[4:7]
	s_waitcnt vmcnt(3)
	v_mfma_f32_16x16x32_bf16 v[0:3], v[116:119], v[112:115], v[0:3]
	v_mfma_f32_16x16x32_bf16 v[4:7], v[120:123], v[112:115], v[4:7]
	s_waitcnt vmcnt(0)
	v_mfma_f32_16x16x32_bf16 v[0:3], v[128:131], v[124:127], v[0:3]
	v_mfma_f32_16x16x32_bf16 v[4:7], v[132:135], v[124:127], v[4:7]
	s_cmpk_eq_i32 s4, 0x1000
	s_cbranch_scc0 .LBB0_757
	v_lshl_add_u32 v13, s2, 7, v20
	v_mov_b64_e32 v[14:15], s[6:7]
	v_mad_i64_i32 v[14:15], s[4:5], v13, s96, v[14:15]
	v_lshl_add_u64 v[14:15], v[14:15], 0, v[198:199]
	s_nop 1
	v_cvt_pk_bf16_f32 v0, v0, v1
	v_cvt_pk_bf16_f32 v1, v2, v3
	v_cvt_pk_bf16_f32 v2, v4, v5
	v_add_co_u32_e32 v4, vcc, 0x2000, v14
	s_add_i32 s2, s2, s3
	s_mov_b64 s[4:5], 0x2400
	v_addc_co_u32_e32 v5, vcc, 0, v15, vcc
	s_cmpk_gt_i32 s2, 0xff
	v_add_u32_e32 v12, s8, v12
	v_lshl_add_u64 v[16:17], v[14:15], 0, s[4:5]
	v_cvt_pk_bf16_f32 v3, v6, v7
	global_store_dwordx2 v[4:5], v[0:1], off offset:1024
	global_store_dwordx2 v[16:17], v[2:3], off offset:32
	s_cbranch_scc0 .LBB0_756

; __global__ void __launch_bounds__(512, 2) hymba_fwd(Params p) {
;     ...
;                 const int nblk = N / 32, nitems = (K / 64) * nblk;
;                 for (int it = gw; it < nitems; it += ngw) {
;                     const int kb = it / nblk, nb = it % nblk, n0 = nb * 32;
;                     const int drow = (mode == 0) ? n0 : ((n0 >> 7) * 256 + (n0 & 127) + (mode == 2 ? 128 : 0));
;                     transpose_item(src, K, N, dst, drow, kb * 64, n0, scr, lane);
;                 }
.LBB0_807:
	s_mul_i32 s101, s2, 0x600
	s_add_i32 s101, s101, s42
	s_and_b32 s101, s101, 0x7ff
	s_cmpk_lg_i32 s65, 0x800
	s_cselect_b32 s101, s42, s101
	s_lshr_b32 s12, s14, 5
	s_lshr_b32 s13, s15, 6
	s_mul_i32 s13, s13, s12
	s_cmp_ge_i32 s101, s13
	s_cbranch_scc1 .LBB0_762
	v_cvt_f32_u32_e32 v4, s12
	v_mov_b32_e32 v1, v199
	s_lshl_b32 s7, s12, 5
	s_sub_i32 s6, 0, s12
	v_rcp_iflag_f32_e32 v4, v4
	s_lshl_b32 s17, s12, 6
	v_lshl_add_u64 v[2:3], s[8:9], 0, v[198:199]
	s_lshl_b32 s8, s101, 5
	v_mul_f32_e32 v4, 0x4f7ffffe, v4
	v_cvt_u32_f32_e32 v6, v4
	v_lshl_add_u64 v[4:5], s[10:11], 0, v[0:1]
	s_sub_i32 s10, 0, s7
	s_lshl_b32 s9, s65, 5
	v_readfirstlane_b32 s7, v6
	s_mul_i32 s6, s6, s7
	s_mul_hi_u32 s6, s7, s6
	s_add_i32 s11, s7, s6
	s_sub_i32 s17, 0, s17
	s_lshl_b32 s18, s101, 6
	s_lshl_b32 s19, s65, 6
	s_mov_b32 s20, s101

; #define LAS __attribute__((address_space(3)))
; DI int get_tid(int wave_s) { int lane; asm volatile("v_mbcnt_lo_u32_b32 %0, -1, 0\n\tv_mbcnt_hi_u32_b32 %0, -1, %0" : "=v"(lane)); return wave_s * 64 + lane; }
; DI unsigned char* WSP(const Params& p) { GAS unsigned char* w = (GAS unsigned char*)p.ws; asm volatile("" : "+s"(w)); return (unsigned char*)w; }
; DI unsigned xb_xcc_id() { return (unsigned)__builtin_amdgcn_s_getreg((3 << 11) | 20) & 0xFu; }
; DI void xcd_barrier(unsigned* bar, volatile LAS unsigned* st, bool leader_thread) {
;     asm volatile("s_waitcnt vmcnt(0)" ::: "memory");
;     __syncthreads();
;     if (leader_thread) {
;         __builtin_amdgcn_s_waitcnt(0);
;         const unsigned x = xb_xcc_id();
;         unsigned nloc = st[0], nx = st[1];
;         if (nloc == 0u) { xcd_barrier_complete(bar, x, gridDim.x, nloc, nx); st[0] = nloc; st[1] = nx; }
; __global__ void __launch_bounds__(512, 2) hymba_fwd(Params p) {
;     ...
;         if (ph + 1 < p.ph_hi) {
;             if (ph == 0) grid.sync();
;             else xcd_barrier((unsigned*)(WSP(p) + WS_BAR), xb_st, get_tid(wave_s) == 0);
.LBB0_843:
	s_and_b64 vcc, exec, s[38:39]
	s_nop 0
	s_mov_b64 s[6:7], s[28:29]
	s_waitcnt vmcnt(0)
	v_mbcnt_lo_u32_b32 v0, -1, 0
	v_mbcnt_hi_u32_b32 v0, -1, v0
	s_waitcnt vmcnt(0)
	v_readlane_b32 s2, v254, 2
	s_waitcnt lgkmcnt(0)
	s_barrier
	v_cmp_eq_u32_e32 vcc, s2, v0
	s_and_saveexec_b64 s[4:5], vcc
	s_cbranch_execz .LBB0_896
	v_readlane_b32 s8, v255, 9
	s_waitcnt vmcnt(0) expcnt(0) lgkmcnt(0)
	s_getreg_b32 s2, hwreg(HW_REG_XCC_ID, 0, 4)
	v_mov_b32_e32 v0, s8
	ds_read_b32 v2, v0
	v_readlane_b32 s8, v255, 10
	s_and_b32 s2, s2, 15
	s_waitcnt lgkmcnt(0)
	v_cmp_ne_u32_e32 vcc, 0, v2
	v_mov_b32_e32 v0, s8
	ds_read_b32 v0, v0
	s_cbranch_vccnz .LBB0_860
	s_add_u32 s8, s6, 0x3a6e3200
	s_addc_u32 s9, s7, 0
	s_add_u32 s10, s6, 0x3a6e3400
	s_addc_u32 s11, s7, 0
	s_add_u32 s12, s6, 0x3a6e3500
	s_addc_u32 s13, s7, 0
	s_add_u32 s14, s6, 0x3a6e3600
	s_addc_u32 s15, s7, 0
	s_add_u32 s16, s6, 0x3a6e3700
	s_addc_u32 s17, s7, 0
	s_add_u32 s18, s6, 0x3a6e3800
	s_addc_u32 s19, s7, 0
	s_add_u32 s20, s6, 0x3a6e3900
	s_addc_u32 s21, s7, 0
	s_add_u32 s22, s6, 0x3a6e3a00
	s_addc_u32 s23, s7, 0
	s_add_u32 s24, s6, 0x3a6e3b00
	s_addc_u32 s25, s7, 0
	s_add_u32 s38, s6, 0x3a6e3c00
	s_addc_u32 s39, s7, 0
	s_add_u32 s48, s6, 0x3a6e3d00
	s_addc_u32 s49, s7, 0
	s_mov_b32 s84, s52
	s_add_u32 s52, s6, 0x3a6e3e00
	s_addc_u32 s53, s7, 0
	s_mov_b32 s90, s54
	s_add_u32 s54, s6, 0x3a6e3f00
	s_addc_u32 s55, s7, 0
	s_add_u32 s56, s6, 0x3a6e4000
	s_addc_u32 s57, s7, 0
	s_add_u32 s60, s6, 0x3a6e4100
	s_addc_u32 s61, s7, 0
	s_add_u32 s62, s6, 0x3a6e4200
	s_addc_u32 s63, s7, 0
	s_add_u32 s78, s6, 0x3a6e4300
	s_addc_u32 s79, s7, 0
	s_mov_b32 s77, 1
	s_branch .LBB0_848

; #define LAS __attribute__((address_space(3)))
; __global__ void __launch_bounds__(512, 2) hymba_fwd(Params p) {
;     extern __shared__ __attribute__((aligned(16))) unsigned char shm[];
;     LAS unsigned char* lds = (LAS unsigned char*)shm;
;     cg::grid_group grid = cg::this_grid();
;     const int G = gridDim.x, bid = blockIdx.x;
;     const int wave_s = __builtin_amdgcn_readfirstlane((int)threadIdx.x >> 6);
	.amdhsa_kernel _Z9hymba_fwd6Params
		.amdhsa_group_segment_fixed_size 0
		.amdhsa_private_segment_fixed_size 0
		.amdhsa_kernarg_size 512
		.amdhsa_user_sgpr_count 2
		.amdhsa_user_sgpr_dispatch_ptr 0
		.amdhsa_user_sgpr_queue_ptr 0
		.amdhsa_user_sgpr_kernarg_segment_ptr 1
		.amdhsa_user_sgpr_dispatch_id 0
		.amdhsa_user_sgpr_kernarg_preload_length 0
		.amdhsa_user_sgpr_kernarg_preload_offset 0
		.amdhsa_user_sgpr_private_segment_size 0
		.amdhsa_uses_dynamic_stack 0
		.amdhsa_enable_private_segment 0
		.amdhsa_system_sgpr_workgroup_id_x 1
		.amdhsa_system_sgpr_workgroup_id_y 0
		.amdhsa_system_sgpr_workgroup_id_z 0
		.amdhsa_system_sgpr_workgroup_info 0
		.amdhsa_system_vgpr_workitem_id 2
		.amdhsa_next_free_vgpr 256
		.amdhsa_next_free_sgpr 102
		.amdhsa_accum_offset 256
		.amdhsa_reserve_vcc 1
		.amdhsa_float_round_mode_32 0
		.amdhsa_float_round_mode_16_64 0
		.amdhsa_float_denorm_mode_32 3
		.amdhsa_float_denorm_mode_16_64 3
		.amdhsa_dx10_clamp 1
		.amdhsa_ieee_mode 1
		.amdhsa_fp16_overflow 0
		.amdhsa_tg_split 0
		.amdhsa_exception_fp_ieee_invalid_op 0
		.amdhsa_exception_fp_denorm_src 0
		.amdhsa_exception_fp_ieee_div_zero 0
		.amdhsa_exception_fp_ieee_overflow 0
		.amdhsa_exception_fp_ieee_underflow 0
		.amdhsa_exception_fp_ieee_inexact 0
		.amdhsa_exception_int_div_zero 0
	.end_amdhsa_kernel

; __global__ void __launch_bounds__(512, 2) hymba_fwd(Params p) {
amdhsa.kernels:
  - .agpr_count:     0
    .args:
      - .offset:         0
        .size:           256
        .value_kind:     by_value
      - .offset:         256
        .size:           4
        .value_kind:     hidden_block_count_x
      - .offset:         260
        .size:           4
        .value_kind:     hidden_block_count_y
      - .offset:         264
        .size:           4
        .value_kind:     hidden_block_count_z
      - .offset:         268
        .size:           2
        .value_kind:     hidden_group_size_x
      - .offset:         270
        .size:           2
        .value_kind:     hidden_group_size_y
      - .offset:         272
        .size:           2
        .value_kind:     hidden_group_size_z
      - .offset:         274
        .size:           2
        .value_kind:     hidden_remainder_x
      - .offset:         276
        .size:           2
        .value_kind:     hidden_remainder_y
      - .offset:         278
        .size:           2
        .value_kind:     hidden_remainder_z
      - .offset:         296
        .size:           8
        .value_kind:     hidden_global_offset_x
      - .offset:         304
        .size:           8
        .value_kind:     hidden_global_offset_y
      - .offset:         312
        .size:           8
        .value_kind:     hidden_global_offset_z
      - .offset:         320
        .size:           2
        .value_kind:     hidden_grid_dims
      - .offset:         344
        .size:           8
        .value_kind:     hidden_multigrid_sync_arg
      - .offset:         376
        .size:           4
        .value_kind:     hidden_dynamic_lds_size
    .group_segment_fixed_size: 0
    .kernarg_segment_align: 8
    .kernarg_segment_size: 512
    .language:       OpenCL C
    .language_version:
      - 2
      - 0
    .max_flat_workgroup_size: 512
    .name:           _Z9hymba_fwd6Params
    .private_segment_fixed_size: 0
    .sgpr_count:     108
    .sgpr_spill_count: 131
    .symbol:         _Z9hymba_fwd6Params.kd
    .uniform_work_group_size: 1
    .uses_dynamic_stack: false
    .vgpr_count:     256
    .vgpr_spill_count: 0
    .wavefront_size: 64
